# phase 2: sample attention moved from wave 1 (2 scan_end chunks) to wave 7 (1 chunk) to shorten the pre-barrier critical path
# baseline (speedup 1.0000x reference)
; template <bool LDSRC>
; __device__ __forceinline__ void attn_core(const Params& p, const int lane, const char* kptr, const int kstride, const char* vptr, const int vstride,
;                                           const int kt0, const int has_prev, const int row_q, const int h_q, const int i_q) {
;     ...
;   const int lo = has_prev ? (i_q + 1) : ((i_q + 1) > 128 ? (i_q + 1) : 128);
;   const unsigned span = (unsigned)(i_q + 128 - lo);
;   const int dbase = q4 * 4 - lo;
;   float mx = -INFINITY;
; #pragma unroll
;   for (int kt = 0; kt < 9; ++kt) {
; #pragma unroll
;     for (int r = 0; r < 4; ++r) {
;       const int d = (kt0 + kt) * 16 + r + dbase;
;       const float v = ((unsigned)d <= span) ? sa[kt][r] : -INFINITY;
;       sa[kt][r] = v; mx = fmaxf(mx, v);
;     }
;   }
; __global__ void __launch_bounds__(512) fwd_megakernel(Params p) {
;     ...
;     for (int i = gw; i < 8 * N_AT; i += NGW) { if ((i & 7) == 1) attn_sample_unit(p, i >> 3, lane); }
.LBB0_543:
	s_or_b64 exec, exec, s[14:15]
	v_bfe_u32 v3, v0, 2, 2
	v_or_b32_e32 v21, 0x4000, v3
	v_sub_u32_e32 v3, v3, v14
	v_readlane_b32 s4, v244, 53
	v_add_u32_e32 v14, 0x7f, v3
	s_movk_i32 s18, 0x80
	v_readlane_b32 s5, v244, 54
	v_cmp_gt_u32_e64 s[6:7], s18, v14
	v_add_u32_e32 v14, 0x7e, v3
	v_lshl_add_u64 v[4:5], s[4:5], 0, v[8:9]
	s_movk_i32 s4, 0xff7f
	v_cmp_gt_u32_e64 s[8:9], s18, v14
	v_add_u32_e32 v14, -1, v3
	v_cmp_lt_u32_e64 s[4:5], s4, v3
	v_cmp_eq_u32_e64 s[10:11], 3, v3
	v_cmp_gt_u32_e64 s[12:13], -12, v3
	v_cmp_gt_u32_e64 s[14:15], s18, v14
	v_add_u32_e32 v14, -2, v3
	v_add_u32_e32 v3, -3, v3
	v_readlane_b32 s28, v244, 0
	v_cmp_gt_u32_e64 s[16:17], s18, v14
	v_cmp_gt_u32_e64 s[18:19], s18, v3
	v_readlane_b32 s30, v244, 2
	v_and_b32_e32 v3, 0x1c0, v0
	v_mbcnt_hi_u32_b32 v23, -1, v185
	v_mov_b32_e32 v9, 0
	v_readlane_b32 s29, v244, 1
	v_readlane_b32 s31, v244, 3
	s_add_u32 s28, s30, 0x7380000
	s_movk_i32 s98, 0x1c0
	v_cmp_eq_u32_e64 s[20:21], s98, v3
	v_and_b32_e32 v3, 64, v23
	v_and_b32_e32 v20, 3, v0
	s_movk_i32 s36, 0x4000
	v_mul_u32_u24_e32 v6, 0x120, v78
	v_mov_b32_e32 v7, v9
	v_mul_u32_u24_e32 v10, 0x120, v80
	v_mov_b32_e32 v11, v9
	v_lshlrev_b32_e32 v12, 8, v78
	v_mov_b32_e32 v83, v9
	v_mov_b32_e32 v13, v9
	s_addc_u32 s29, s31, 0
	s_mov_b64 s[30:31], 0
	s_mov_b32 s37, 0x9000
	s_movk_i32 s38, 0x1800
	s_movk_i32 s39, 0x4800
	s_movk_i32 s40, 0x1000
	s_movk_i32 s41, 0x2000
	s_movk_i32 s42, 0x3000
	s_movk_i32 s43, 0x5000
	s_movk_i32 s44, 0x6000
	s_movk_i32 s45, 0x7000
	s_mov_b32 s46, 0x8000
	s_mov_b32 s47, 0xff800000
	s_movk_i32 s48, 0x7ff
	v_lshlrev_b32_e32 v14, 1, v8
	v_mov_b32_e32 v22, 0xff800000
	v_xor_b32_e32 v26, 16, v23
	v_add_u32_e32 v27, 64, v3
	v_xor_b32_e32 v28, 32, v23
	v_mov_b32_e32 v29, v182
	s_branch .LBB0_545
